# GEMM phase prologues: second K-tile DMA issued before waiting for the first (stagger barrier moved after the issue); dwconv tile rows loaded 8 at a time
# baseline (speedup 1.0000x reference)
.LBB0_116:
	s_waitcnt lgkmcnt(6)
	v_add_f32_e32 v8, v8, v10
	v_fmamk_f32 v8, v8, 0x3a800000, v240
	v_rsq_f32_e32 v164, v8
	s_waitcnt lgkmcnt(5)
	v_add_f32_e32 v8, v15, v17
	v_fmamk_f32 v8, v8, 0x3a800000, v240
	v_rsq_f32_e32 v163, v8
	s_waitcnt lgkmcnt(4)
	v_add_f32_e32 v8, v13, v16
	v_fmamk_f32 v8, v8, 0x3a800000, v240
	v_rsq_f32_e32 v162, v8
	s_waitcnt lgkmcnt(3)
	v_add_f32_e32 v8, v12, v14
	v_fmamk_f32 v8, v8, 0x3a800000, v240
	v_rsq_f32_e32 v161, v8
	s_waitcnt lgkmcnt(2)
	v_add_f32_e32 v8, v21, v23
	v_fmamk_f32 v8, v8, 0x3a800000, v240
	v_rsq_f32_e32 v160, v8
	s_waitcnt lgkmcnt(1)
	v_add_f32_e32 v8, v19, v22
	v_fmamk_f32 v8, v8, 0x3a800000, v240
	v_add_f32_e32 v9, v9, v11
	v_rsq_f32_e32 v154, v8
	s_waitcnt lgkmcnt(0)
	v_add_f32_e32 v8, v18, v20
	v_fmamk_f32 v9, v9, 0x3a800000, v240
	v_fmamk_f32 v8, v8, 0x3a800000, v240
	v_rsq_f32_e32 v165, v9
	v_rsq_f32_e32 v151, v8
	v_and_b32_e32 v8, 15, v7
	v_and_b32_e32 v9, 48, v7
	v_lshlrev_b32_e32 v7, 2, v7
	v_mov_b32_e32 v143, v1
	s_and_b32 s59, s6, 3
	v_lshl_or_b32 v8, v8, 6, v9
	s_lshl_b32 s5, s5, 13
	v_and_b32_e32 v7, 32, v7
	v_lshl_add_u64 v[24:25], s[36:37], 0, v[142:143]
	v_mov_b32_e32 v139, v1
	v_bitop3_b32 v10, v8, s5, v7 bitop3:0xde
	s_lshl_b32 s5, s59, 12
	v_lshl_add_u64 v[26:27], s[36:37], 0, v[138:139]
	v_mov_b32_e32 v145, v1
	v_bitop3_b32 v150, v8, s5, v7 bitop3:0xde
	s_add_i32 m0, s52, 0x18000
	v_lshl_add_u64 v[8:9], v[24:25], 0, s[84:85]
	v_lshl_add_u64 v[28:29], s[10:11], 0, v[144:145]
	v_mov_b32_e32 v141, v1
	global_load_lds_dwordx4 v[8:9], off
	v_lshl_add_u64 v[8:9], v[26:27], 0, s[84:85]
	s_add_i32 m0, s52, 0x1a000
	s_add_i32 s60, s52, 0x8000
	s_add_i32 s61, s52, 0xa000
	v_lshl_add_u64 v[30:31], s[10:11], 0, v[140:141]
	global_load_lds_dwordx4 v[8:9], off
	v_lshl_add_u64 v[8:9], v[28:29], 0, s[84:85]
	s_mov_b32 m0, s60
	s_add_u32 s6, s36, 0x40080
	global_load_lds_dwordx4 v[8:9], off
	v_lshl_add_u64 v[8:9], v[30:31], 0, s[84:85]
	s_mov_b32 m0, s61
	s_addc_u32 s7, s37, 0
	global_load_lds_dwordx4 v[8:9], off
	s_add_i32 m0, s52, 0x1c000
	v_lshl_add_u64 v[8:9], s[6:7], 0, v[142:143]
	global_load_lds_dwordx4 v[8:9], off
	v_lshl_add_u64 v[8:9], s[6:7], 0, v[138:139]
	s_add_i32 m0, s52, 0x1e000
	v_lshlrev_b32_e32 v7, 14, v5
	global_load_lds_dwordx4 v[8:9], off
	s_cselect_b32 s100, 1, 0
	s_cmp_lt_u32 s97, 0x100
	s_cbranch_scc1 .Lstg_skip_0
	s_barrier
.Lstg_skip_0:
	s_cmp_lg_u32 s100, 0
	s_waitcnt vmcnt(8)
	s_barrier
	v_and_b32_e32 v7, 0xffff8000, v7
	v_lshl_add_u32 v4, v4, 11, v7
	v_and_b32_e32 v5, 1, v5
	v_lshl_or_b32 v4, v5, 6, v4
	v_lshl_add_u32 v146, v6, 1, v4
	v_lshlrev_b32_e32 v4, 14, v0
	v_and_b32_e32 v4, 0xffff8000, v4
	s_waitcnt vmcnt(6)
	v_lshl_add_u32 v2, v2, 11, v4
	v_and_b32_e32 v0, 1, v0
	s_cmpk_lt_u32 s4, 0x100
	v_lshl_or_b32 v0, v0, 6, v2
	v_readlane_b32 s6, v253, 7
	s_cselect_b64 s[4:5], -1, 0
	v_mov_b32_e32 v147, v1
	v_lshl_add_u32 v148, v3, 1, v0
	v_mov_b32_e32 v149, v1
	s_mov_b32 s86, 0
	v_add_u32_e32 v152, 0, v10
	v_readlane_b32 s20, v253, 2
	s_mov_b32 s21, s6
	s_barrier
	v_readlane_b32 s7, v253, 8
	s_branch .LBB0_119

.LBB0_139:
	v_readlane_b32 s48, v253, 15
	v_mov_b32_e32 v147, v1
	v_readlane_b32 s49, v253, 16
	v_mov_b32_e32 v143, v1
	v_mov_b32_e32 v149, v1
	v_lshl_add_u64 v[8:9], s[48:49], 0, v[146:147]
	v_lshl_add_u64 v[10:11], s[48:49], 0, v[142:143]
	s_add_i32 m0, s21, 0x18000
	v_lshl_add_u64 v[8:9], v[8:9], 0, s[84:85]
	v_lshl_add_u64 v[12:13], s[40:41], 0, v[148:149]
	v_mov_b32_e32 v145, v1
	global_load_lds_dwordx4 v[8:9], off
	v_lshl_add_u64 v[8:9], v[10:11], 0, s[84:85]
	s_add_i32 m0, s21, 0x1a000
	s_add_i32 s52, s21, 0x8000
	v_lshl_add_u64 v[14:15], s[40:41], 0, v[144:145]
	global_load_lds_dwordx4 v[8:9], off
	v_lshl_add_u64 v[8:9], v[12:13], 0, s[84:85]
	s_mov_b32 m0, s52
	s_add_i32 s53, s21, 0xa000
	v_readlane_b32 s6, v253, 17
	global_load_lds_dwordx4 v[8:9], off
	v_lshl_add_u64 v[8:9], v[14:15], 0, s[84:85]
	s_mov_b32 m0, s53
	v_readlane_b32 s7, v253, 18
	global_load_lds_dwordx4 v[8:9], off
	s_add_i32 m0, s21, 0x1c000
	v_lshl_add_u64 v[8:9], s[6:7], 0, v[146:147]
	global_load_lds_dwordx4 v[8:9], off
	v_lshl_add_u64 v[8:9], s[6:7], 0, v[142:143]
	s_add_i32 m0, s21, 0x1e000
	v_and_b32_e32 v16, 15, v7
	global_load_lds_dwordx4 v[8:9], off
	s_cselect_b32 s100, 1, 0
	s_cmp_lt_u32 s97, 0x100
	s_cbranch_scc1 .Lstg_skip_1
	s_barrier
.Lstg_skip_1:
	s_cmp_lg_u32 s100, 0
	s_waitcnt vmcnt(8)
	s_barrier
	v_and_b32_e32 v17, 48, v7
	v_lshlrev_b32_e32 v7, 2, v7
	s_and_b32 s25, s5, 3
	v_lshl_or_b32 v16, v16, 6, v17
	s_lshl_b32 s5, s19, 13
	v_and_b32_e32 v7, 32, v7
	v_bitop3_b32 v17, v16, s5, v7 bitop3:0xde
	s_lshl_b32 s5, s25, 12
	v_bitop3_b32 v159, v16, s5, v7 bitop3:0xde
	v_lshlrev_b32_e32 v7, 14, v5
	v_and_b32_e32 v7, 0xffff8000, v7
	v_lshl_add_u32 v4, v4, 11, v7
	v_and_b32_e32 v5, 1, v5
	v_lshl_or_b32 v4, v5, 6, v4
	v_lshl_add_u32 v150, v6, 1, v4
	v_lshlrev_b32_e32 v4, 14, v0
	v_and_b32_e32 v4, 0xffff8000, v4
	s_waitcnt vmcnt(6)
	v_lshl_add_u32 v2, v2, 11, v4
	v_and_b32_e32 v0, 1, v0
	s_cmpk_lt_u32 s4, 0x100
	v_lshl_or_b32 v0, v0, 6, v2
	v_readlane_b32 s6, v253, 35
	s_cselect_b64 s[4:5], -1, 0
	v_mov_b32_e32 v151, v1
	v_lshl_add_u32 v152, v3, 1, v0
	v_mov_b32_e32 v153, v1
	s_mov_b32 s54, 0
	v_add_u32_e32 v161, 0, v17
	v_readlane_b32 s55, v253, 5
	s_mov_b32 s26, s6
	s_barrier
	v_readlane_b32 s7, v253, 36
	s_branch .LBB0_142

.LBB0_163:
	v_mov_b32_e32 v151, v1
	v_lshl_add_u64 v[8:9], s[40:41], 0, v[150:151]
	v_mov_b32_e32 v147, v1
	v_readlane_b32 s10, v253, 63
	v_and_b32_e32 v16, 15, v7
	v_and_b32_e32 v17, 48, v7
	v_lshlrev_b32_e32 v7, 2, v7
	v_lshl_add_u64 v[10:11], s[40:41], 0, v[146:147]
	v_mov_b32_e32 v153, v1
	v_readlane_b32 s11, v254, 0
	s_and_b32 s58, s1, 3
	v_lshl_or_b32 v16, v16, 6, v17
	s_lshl_b32 s1, s50, 13
	v_and_b32_e32 v7, 32, v7
	s_add_i32 m0, s52, 0x18000
	v_lshl_add_u64 v[8:9], v[8:9], 0, s[84:85]
	v_lshl_add_u64 v[12:13], s[10:11], 0, v[152:153]
	v_mov_b32_e32 v149, v1
	v_bitop3_b32 v17, v16, s1, v7 bitop3:0xde
	s_lshl_b32 s1, s58, 12
	global_load_lds_dwordx4 v[8:9], off
	v_lshl_add_u64 v[8:9], v[10:11], 0, s[84:85]
	s_add_i32 m0, s52, 0x1a000
	s_add_i32 s59, s52, 0x8000
	s_add_i32 s60, s52, 0xa000
	v_lshl_add_u64 v[14:15], s[10:11], 0, v[148:149]
	global_load_lds_dwordx4 v[8:9], off
	v_lshl_add_u64 v[8:9], v[12:13], 0, s[84:85]
	s_mov_b32 m0, s59
	s_add_u32 s4, s40, 0x40080
	global_load_lds_dwordx4 v[8:9], off
	v_lshl_add_u64 v[8:9], v[14:15], 0, s[84:85]
	s_mov_b32 m0, s60
	s_addc_u32 s5, s41, 0
	global_load_lds_dwordx4 v[8:9], off
	s_add_i32 m0, s52, 0x1c000
	v_lshl_add_u64 v[8:9], s[4:5], 0, v[150:151]
	global_load_lds_dwordx4 v[8:9], off
	v_lshl_add_u64 v[8:9], s[4:5], 0, v[146:147]
	s_add_i32 m0, s52, 0x1e000
	v_bitop3_b32 v160, v16, s1, v7 bitop3:0xde
	global_load_lds_dwordx4 v[8:9], off
	s_cselect_b32 s100, 1, 0
	s_cmp_lt_u32 s97, 0x100
	s_cbranch_scc1 .Lstg_skip_2
	s_barrier
.Lstg_skip_2:
	s_cmp_lg_u32 s100, 0
	s_waitcnt vmcnt(8)
	s_barrier
	v_lshlrev_b32_e32 v7, 14, v5
	v_and_b32_e32 v7, 0xffff8000, v7
	v_lshl_add_u32 v4, v4, 11, v7
	v_and_b32_e32 v5, 1, v5
	v_lshl_or_b32 v4, v5, 6, v4
	v_lshl_add_u32 v154, v6, 1, v4
	v_lshlrev_b32_e32 v4, 14, v0
	v_and_b32_e32 v4, 0xffff8000, v4
	s_waitcnt vmcnt(6)
	v_lshl_add_u32 v2, v2, 11, v4
	v_and_b32_e32 v0, 1, v0
	s_cmpk_lt_u32 s0, 0x100
	v_lshl_or_b32 v0, v0, 6, v2
	v_readlane_b32 s0, v253, 58
	s_cselect_b64 s[82:83], -1, 0
	v_mov_b32_e32 v155, v1
	v_lshl_add_u32 v156, v3, 1, v0
	v_mov_b32_e32 v157, v1
	s_mov_b32 s61, 0
	v_add_u32_e32 v161, 0, v17
	v_readlane_b32 s19, v253, 62
	s_mov_b32 s20, s0
	s_barrier
	v_readlane_b32 s1, v253, 59
	s_branch .LBB0_166

.LBB0_261:
	v_lshl_add_u64 v[12:13], s[48:49], 0, v[0:1]
	v_mov_b32_e32 v195, v1
	v_readlane_b32 s50, v253, 37
	v_and_b32_e32 v11, 48, v7
	v_lshlrev_b32_e32 v20, 6, v7
	s_movk_i32 s3, 0x3c0
	v_lshlrev_b32_e32 v7, 2, v7
	v_lshl_add_u64 v[14:15], s[48:49], 0, v[194:195]
	v_mov_b32_e32 v199, v1
	v_readlane_b32 s51, v253, 38
	s_and_b32 s55, s6, 3
	s_lshl_b32 s58, s5, 6
	s_lshl_b32 s5, s5, 13
	v_and_or_b32 v11, v20, s3, v11
	v_and_b32_e32 v7, 32, v7
	s_add_i32 m0, s20, 0x18000
	v_lshl_add_u64 v[12:13], v[12:13], 0, s[84:85]
	v_lshl_add_u64 v[16:17], s[50:51], 0, v[198:199]
	v_mov_b32_e32 v197, v1
	v_bitop3_b32 v20, v11, s5, v7 bitop3:0xde
	s_lshl_b32 s59, s55, 5
	s_lshl_b32 s5, s55, 12
	global_load_lds_dwordx4 v[12:13], off
	v_lshl_add_u64 v[12:13], v[14:15], 0, s[84:85]
	s_add_i32 m0, s20, 0x1a000
	s_add_i32 s60, s20, 0x8000
	s_add_i32 s61, s20, 0xa000
	v_lshl_add_u64 v[18:19], s[50:51], 0, v[196:197]
	global_load_lds_dwordx4 v[12:13], off
	v_lshl_add_u64 v[12:13], v[16:17], 0, s[16:17]
	s_mov_b32 m0, s60
	s_add_u32 s6, s48, 0x100080
	global_load_lds_dwordx4 v[12:13], off
	v_lshl_add_u64 v[12:13], v[18:19], 0, s[16:17]
	s_mov_b32 m0, s61
	s_addc_u32 s7, s49, 0
	global_load_lds_dwordx4 v[12:13], off
	s_add_i32 m0, s20, 0x1c000
	v_lshl_add_u64 v[12:13], s[6:7], 0, v[0:1]
	global_load_lds_dwordx4 v[12:13], off
	v_lshl_add_u64 v[12:13], s[6:7], 0, v[194:195]
	s_add_i32 m0, s20, 0x1e000
	v_bitop3_b32 v242, v11, s5, v7 bitop3:0xde
	global_load_lds_dwordx4 v[12:13], off
	s_cselect_b32 s100, 1, 0
	s_cmp_lt_u32 s97, 0x100
	s_cbranch_scc1 .Lstg_skip_3
	s_barrier
.Lstg_skip_3:
	s_cmp_lg_u32 s100, 0
	s_waitcnt vmcnt(8)
	s_barrier
	v_lshlrev_b32_e32 v7, 10, v8
	v_lshlrev_b32_e32 v3, 10, v3
	v_and_b32_e32 v7, 0xfffe0000, v7
	v_and_b32_e32 v3, 0xfffe0000, v3
	s_waitcnt vmcnt(6)
	v_lshl_add_u32 v6, v6, 10, v7
	v_lshl_add_u32 v2, v2, 10, v3
	s_cmpk_lt_u32 s4, 0x100
	v_or_b32_e32 v6, v6, v9
	v_or_b32_e32 v2, v2, v4
	v_readlane_b32 s6, v253, 35
	s_cselect_b64 s[4:5], -1, 0
	v_add_u32_e32 v200, v6, v10
	v_mov_b32_e32 v201, v1
	v_add_u32_e32 v202, v2, v5
	v_mov_b32_e32 v203, v1
	s_mov_b32 s24, 0
	v_add_u32_e32 v243, 0, v20
	v_readlane_b32 s25, v253, 5
	s_mov_b32 s26, s6
	s_barrier
	v_readlane_b32 s7, v253, 36
	s_branch .LBB0_264

.LBB0_298:
	v_readlane_b32 s42, v254, 41
	v_and_b32_e32 v3, 15, v2
	v_and_b32_e32 v12, 48, v2
	v_lshlrev_b32_e32 v2, 2, v2
	v_readlane_b32 s43, v254, 42
	s_and_b32 s86, s5, 3
	v_lshl_or_b32 v3, v3, 6, v12
	s_lshl_b32 s5, s25, 13
	v_and_b32_e32 v2, 32, v2
	v_lshl_add_u64 v[4:5], s[42:43], 0, v[0:1]
	v_mov_b32_e32 v131, v1
	v_readlane_b32 s44, v254, 37
	v_bitop3_b32 v12, v3, s5, v2 bitop3:0xde
	s_lshl_b32 s5, s86, 12
	v_lshl_add_u64 v[6:7], s[42:43], 0, v[130:131]
	v_mov_b32_e32 v135, v1
	v_readlane_b32 s45, v254, 38
	v_bitop3_b32 v136, v3, s5, v2 bitop3:0xde
	s_add_i32 m0, s21, 0x18000
	v_lshl_add_u64 v[2:3], v[4:5], 0, s[84:85]
	v_lshl_add_u64 v[8:9], s[44:45], 0, v[134:135]
	v_mov_b32_e32 v133, v1
	global_load_lds_dwordx4 v[2:3], off
	v_lshl_add_u64 v[2:3], v[6:7], 0, s[84:85]
	s_add_i32 m0, s21, 0x1a000
	s_add_i32 s26, s21, 0x8000
	v_lshl_add_u64 v[10:11], s[44:45], 0, v[132:133]
	global_load_lds_dwordx4 v[2:3], off
	v_lshl_add_u64 v[2:3], v[8:9], 0, s[84:85]
	s_mov_b32 m0, s26
	s_add_i32 s27, s21, 0xa000
	v_readlane_b32 s6, v254, 43
	global_load_lds_dwordx4 v[2:3], off
	v_lshl_add_u64 v[2:3], v[10:11], 0, s[84:85]
	s_mov_b32 m0, s27
	v_readlane_b32 s7, v254, 44
	global_load_lds_dwordx4 v[2:3], off
	s_add_i32 m0, s21, 0x1c000
	v_lshl_add_u64 v[2:3], s[6:7], 0, v[0:1]
	global_load_lds_dwordx4 v[2:3], off
	v_lshl_add_u64 v[2:3], s[6:7], 0, v[130:131]
	s_add_i32 m0, s21, 0x1e000
	s_cmpk_lt_u32 s4, 0x100
	global_load_lds_dwordx4 v[2:3], off
	s_cselect_b32 s100, 1, 0
	s_cmp_lt_u32 s97, 0x100
	s_cbranch_scc1 .Lstg_skip_4
	s_barrier
.Lstg_skip_4:
	s_cmp_lg_u32 s100, 0
	s_waitcnt vmcnt(8)
	s_barrier
	s_waitcnt vmcnt(6)
	v_readlane_b32 s6, v253, 35
	s_mov_b32 s28, 0
	s_cselect_b64 s[4:5], -1, 0
	v_add_u32_e32 v137, 0, v12
	v_readlane_b32 s29, v253, 5
	s_mov_b32 s30, s6
	s_barrier
	v_readlane_b32 s7, v253, 36
	s_branch .LBB0_301

.LBB0_398:
	v_mov_b32_e32 v147, v1
	v_lshl_add_u64 v[8:9], s[48:49], 0, v[146:147]
	v_mov_b32_e32 v143, v1
	v_readlane_b32 s44, v253, 23
	v_and_b32_e32 v16, 15, v7
	v_and_b32_e32 v17, 48, v7
	v_lshlrev_b32_e32 v7, 2, v7
	v_lshl_add_u64 v[10:11], s[48:49], 0, v[142:143]
	v_mov_b32_e32 v149, v1
	v_readlane_b32 s45, v253, 24
	s_and_b32 s52, s7, 3
	v_lshl_or_b32 v16, v16, 6, v17
	s_lshl_b32 s7, s20, 13
	v_and_b32_e32 v7, 32, v7
	s_add_i32 m0, s22, 0x18000
	v_lshl_add_u64 v[8:9], v[8:9], 0, s[84:85]
	v_lshl_add_u64 v[12:13], s[44:45], 0, v[148:149]
	v_mov_b32_e32 v145, v1
	v_bitop3_b32 v17, v16, s7, v7 bitop3:0xde
	s_lshl_b32 s7, s52, 12
	global_load_lds_dwordx4 v[8:9], off
	v_lshl_add_u64 v[8:9], v[10:11], 0, s[84:85]
	s_add_i32 m0, s22, 0x1a000
	s_add_i32 s53, s22, 0x8000
	s_add_i32 s54, s22, 0xa000
	v_lshl_add_u64 v[14:15], s[44:45], 0, v[144:145]
	global_load_lds_dwordx4 v[8:9], off
	v_lshl_add_u64 v[8:9], v[12:13], 0, s[84:85]
	s_mov_b32 m0, s53
	s_add_u32 s8, s48, 0x40080
	global_load_lds_dwordx4 v[8:9], off
	v_lshl_add_u64 v[8:9], v[14:15], 0, s[84:85]
	s_mov_b32 m0, s54
	s_addc_u32 s9, s49, 0
	global_load_lds_dwordx4 v[8:9], off
	s_add_i32 m0, s22, 0x1c000
	v_lshl_add_u64 v[8:9], s[8:9], 0, v[146:147]
	global_load_lds_dwordx4 v[8:9], off
	v_lshl_add_u64 v[8:9], s[8:9], 0, v[142:143]
	s_add_i32 m0, s22, 0x1e000
	v_bitop3_b32 v158, v16, s7, v7 bitop3:0xde
	global_load_lds_dwordx4 v[8:9], off
	s_cselect_b32 s100, 1, 0
	s_cmp_lt_u32 s97, 0x100
	s_cbranch_scc1 .Lstg_skip_5
	s_barrier
.Lstg_skip_5:
	s_cmp_lg_u32 s100, 0
	s_waitcnt vmcnt(8)
	s_barrier
	v_lshlrev_b32_e32 v7, 14, v5
	v_and_b32_e32 v7, 0xffff8000, v7
	v_lshl_add_u32 v4, v4, 11, v7
	v_and_b32_e32 v5, 1, v5
	v_lshl_or_b32 v4, v5, 6, v4
	v_lshl_add_u32 v150, v6, 1, v4
	v_lshlrev_b32_e32 v4, 14, v0
	v_and_b32_e32 v4, 0xffff8000, v4
	s_waitcnt vmcnt(6)
	v_lshl_add_u32 v2, v2, 11, v4
	v_and_b32_e32 v0, 1, v0
	s_cmpk_lt_u32 s6, 0x100
	v_lshl_or_b32 v0, v0, 6, v2
	v_readlane_b32 s2, v253, 35
	s_cselect_b64 s[6:7], -1, 0
	v_mov_b32_e32 v151, v1
	v_lshl_add_u32 v152, v3, 1, v0
	v_mov_b32_e32 v153, v1
	s_mov_b32 s55, 0
	v_add_u32_e32 v159, 0, v17
	v_readlane_b32 s58, v253, 5
	s_mov_b32 s26, s2
	s_barrier
	v_readlane_b32 s3, v253, 36
	s_branch .LBB0_401

.LBB0_612:
	v_readlane_b32 s44, v254, 49
	v_readlane_b32 s45, v254, 50
	v_mov_b32_e32 v147, v1
	v_readlane_b32 s40, v253, 43
	v_lshl_add_u64 v[26:27], s[44:45], 0, v[0:1]
	v_lshl_add_u64 v[28:29], s[44:45], 0, v[146:147]
	v_mov_b32_e32 v151, v1
	v_readlane_b32 s41, v253, 44
	s_add_i32 m0, s21, 0x18000
	v_lshl_add_u64 v[26:27], v[26:27], 0, s[84:85]
	v_lshl_add_u64 v[30:31], s[40:41], 0, v[150:151]
	v_mov_b32_e32 v149, v1
	global_load_lds_dwordx4 v[26:27], off
	v_lshl_add_u64 v[26:27], v[28:29], 0, s[84:85]
	s_add_i32 m0, s21, 0x1a000
	s_add_i32 s24, s21, 0x8000
	v_lshl_add_u64 v[32:33], s[40:41], 0, v[148:149]
	global_load_lds_dwordx4 v[26:27], off
	v_lshl_add_u64 v[26:27], v[30:31], 0, s[84:85]
	s_mov_b32 m0, s24
	s_add_i32 s25, s21, 0xa000
	v_readlane_b32 s6, v254, 51
	global_load_lds_dwordx4 v[26:27], off
	v_lshl_add_u64 v[26:27], v[32:33], 0, s[84:85]
	s_mov_b32 m0, s25
	v_readlane_b32 s7, v254, 52
	global_load_lds_dwordx4 v[26:27], off
	s_add_i32 m0, s21, 0x1c000
	v_lshl_add_u64 v[26:27], s[6:7], 0, v[0:1]
	global_load_lds_dwordx4 v[26:27], off
	v_lshl_add_u64 v[26:27], s[6:7], 0, v[146:147]
	s_add_i32 m0, s21, 0x1e000
	s_waitcnt lgkmcnt(0)
	v_add_f32_e32 v9, v9, v11
	global_load_lds_dwordx4 v[26:27], off
	s_cselect_b32 s100, 1, 0
	s_cmp_lt_u32 s97, 0x100
	s_cbranch_scc1 .Lstg_skip_6
	s_barrier
.Lstg_skip_6:
	s_cmp_lg_u32 s100, 0
	s_waitcnt vmcnt(8)
	s_barrier
	v_fmamk_f32 v9, v9, 0x3a800000, v240
	v_rsq_f32_e32 v168, v9
	v_add_f32_e32 v9, v16, v18
	v_fmamk_f32 v9, v9, 0x3a800000, v240
	v_rsq_f32_e32 v166, v9
	v_add_f32_e32 v9, v14, v17
	v_fmamk_f32 v9, v9, 0x3a800000, v240
	v_rsq_f32_e32 v164, v9
	v_add_f32_e32 v9, v13, v15
	v_fmamk_f32 v9, v9, 0x3a800000, v240
	v_rsq_f32_e32 v162, v9
	v_add_f32_e32 v9, v22, v24
	v_fmamk_f32 v9, v9, 0x3a800000, v240
	v_rsq_f32_e32 v160, v9
	v_add_f32_e32 v9, v20, v23
	v_fmamk_f32 v9, v9, 0x3a800000, v240
	v_add_f32_e32 v10, v10, v12
	v_rsq_f32_e32 v158, v9
	v_add_f32_e32 v9, v19, v21
	v_fmamk_f32 v10, v10, 0x3a800000, v240
	v_fmamk_f32 v9, v9, 0x3a800000, v240
	v_rsq_f32_e32 v170, v10
	v_rsq_f32_e32 v156, v9
	v_and_b32_e32 v9, 15, v3
	v_and_b32_e32 v10, 48, v3
	v_lshlrev_b32_e32 v3, 2, v3
	s_and_b32 s52, s5, 3
	v_lshl_or_b32 v9, v9, 6, v10
	s_lshl_b32 s5, s19, 13
	v_and_b32_e32 v3, 32, v3
	v_bitop3_b32 v10, v9, s5, v3 bitop3:0xde
	s_lshl_b32 s5, s52, 12
	v_bitop3_b32 v157, v9, s5, v3 bitop3:0xde
	v_lshlrev_b32_e32 v3, 14, v7
	v_and_b32_e32 v3, 0xffff8000, v3
	v_lshl_add_u32 v3, v6, 11, v3
	v_and_b32_e32 v6, 1, v7
	v_lshl_or_b32 v3, v6, 6, v3
	v_lshl_add_u32 v152, v8, 1, v3
	v_lshlrev_b32_e32 v3, 14, v2
	v_and_b32_e32 v3, 0xffff8000, v3
	s_waitcnt vmcnt(6)
	v_lshl_add_u32 v3, v4, 11, v3
	v_and_b32_e32 v2, 1, v2
	s_cmpk_lt_u32 s4, 0x100
	v_lshl_or_b32 v2, v2, 6, v3
	v_readlane_b32 s6, v253, 47
	s_cselect_b64 s[4:5], -1, 0
	v_mov_b32_e32 v153, v1
	v_lshl_add_u32 v154, v5, 1, v2
	v_mov_b32_e32 v155, v1
	s_mov_b32 s53, 0
	v_add_u32_e32 v159, 0, v10
	v_readlane_b32 s55, v253, 34
	s_mov_b32 s54, s6
	s_barrier
	v_readlane_b32 s7, v253, 48
	s_branch .LBB0_615

.LBB0_720:
	s_lshl_b32 s9, s8, 5
	s_and_saveexec_b64 s[0:1], s[40:41]
	s_cbranch_execz .LBB0_725
	s_ashr_i32 s4, s9, 31
	s_lshr_b32 s4, s4, 21
	s_add_i32 s4, s9, s4
	s_and_b32 s4, s4, 0xfffff800
	s_sub_i32 s10, s4, s9
	s_add_i32 s10, s10, 29
	s_sub_i32 s11, s9, 30
	v_lshrrev_b32_e32 v44, 7, v188
	v_and_b32_e32 v0, 0x7f, v188
	v_lshlrev_b32_e32 v0, 4, v0
	s_movk_i32 s4, 0x100
	v_cmp_gt_u32_e64 s[12:13], s4, v188
	s_mov_b64 s[4:5], exec
	v_add_u32_e32 v42, 0, v44
	v_mov_b32_e32 v8, 0
	v_mov_b32_e32 v9, 0
	v_mov_b32_e32 v10, 0
	v_mov_b32_e32 v11, 0
	v_cmp_lt_i32_e32 vcc, s10, v42
	s_and_saveexec_b64 s[6:7], vcc
	v_add_u32_e32 v40, s11, v42
	v_ashrrev_i32_e32 v41, 31, v40
	v_lshlrev_b64 v[40:41], 11, v[40:41]
	v_lshl_add_u64 v[40:41], s[62:63], 0, v[40:41]
	v_lshl_add_u64 v[40:41], v[40:41], 0, v[0:1]
	global_load_dwordx4 v[8:11], v[40:41], off
	s_mov_b64 exec, s[4:5]
	v_add_u32_e32 v42, 4, v44
	v_mov_b32_e32 v12, 0
	v_mov_b32_e32 v13, 0
	v_mov_b32_e32 v14, 0
	v_mov_b32_e32 v15, 0
	v_cmp_lt_i32_e32 vcc, s10, v42
	s_and_saveexec_b64 s[6:7], vcc
	v_add_u32_e32 v40, s11, v42
	v_ashrrev_i32_e32 v41, 31, v40
	v_lshlrev_b64 v[40:41], 11, v[40:41]
	v_lshl_add_u64 v[40:41], s[62:63], 0, v[40:41]
	v_lshl_add_u64 v[40:41], v[40:41], 0, v[0:1]
	global_load_dwordx4 v[12:15], v[40:41], off
	s_mov_b64 exec, s[4:5]
	v_add_u32_e32 v42, 8, v44
	v_mov_b32_e32 v16, 0
	v_mov_b32_e32 v17, 0
	v_mov_b32_e32 v18, 0
	v_mov_b32_e32 v19, 0
	v_cmp_lt_i32_e32 vcc, s10, v42
	s_and_saveexec_b64 s[6:7], vcc
	v_add_u32_e32 v40, s11, v42
	v_ashrrev_i32_e32 v41, 31, v40
	v_lshlrev_b64 v[40:41], 11, v[40:41]
	v_lshl_add_u64 v[40:41], s[62:63], 0, v[40:41]
	v_lshl_add_u64 v[40:41], v[40:41], 0, v[0:1]
	global_load_dwordx4 v[16:19], v[40:41], off
	s_mov_b64 exec, s[4:5]
	v_add_u32_e32 v42, 12, v44
	v_mov_b32_e32 v20, 0
	v_mov_b32_e32 v21, 0
	v_mov_b32_e32 v22, 0
	v_mov_b32_e32 v23, 0
	v_cmp_lt_i32_e32 vcc, s10, v42
	s_and_saveexec_b64 s[6:7], vcc
	v_add_u32_e32 v40, s11, v42
	v_ashrrev_i32_e32 v41, 31, v40
	v_lshlrev_b64 v[40:41], 11, v[40:41]
	v_lshl_add_u64 v[40:41], s[62:63], 0, v[40:41]
	v_lshl_add_u64 v[40:41], v[40:41], 0, v[0:1]
	global_load_dwordx4 v[20:23], v[40:41], off
	s_mov_b64 exec, s[4:5]
	v_add_u32_e32 v42, 16, v44
	v_mov_b32_e32 v24, 0
	v_mov_b32_e32 v25, 0
	v_mov_b32_e32 v26, 0
	v_mov_b32_e32 v27, 0
	v_cmp_lt_i32_e32 vcc, s10, v42
	s_and_saveexec_b64 s[6:7], vcc
	v_add_u32_e32 v40, s11, v42
	v_ashrrev_i32_e32 v41, 31, v40
	v_lshlrev_b64 v[40:41], 11, v[40:41]
	v_lshl_add_u64 v[40:41], s[62:63], 0, v[40:41]
	v_lshl_add_u64 v[40:41], v[40:41], 0, v[0:1]
	global_load_dwordx4 v[24:27], v[40:41], off
	s_mov_b64 exec, s[4:5]
	v_add_u32_e32 v42, 20, v44
	v_mov_b32_e32 v28, 0
	v_mov_b32_e32 v29, 0
	v_mov_b32_e32 v30, 0
	v_mov_b32_e32 v31, 0
	v_cmp_lt_i32_e32 vcc, s10, v42
	s_and_saveexec_b64 s[6:7], vcc
	v_add_u32_e32 v40, s11, v42
	v_ashrrev_i32_e32 v41, 31, v40
	v_lshlrev_b64 v[40:41], 11, v[40:41]
	v_lshl_add_u64 v[40:41], s[62:63], 0, v[40:41]
	v_lshl_add_u64 v[40:41], v[40:41], 0, v[0:1]
	global_load_dwordx4 v[28:31], v[40:41], off
	s_mov_b64 exec, s[4:5]
	v_add_u32_e32 v42, 24, v44
	v_mov_b32_e32 v32, 0
	v_mov_b32_e32 v33, 0
	v_mov_b32_e32 v34, 0
	v_mov_b32_e32 v35, 0
	v_cmp_lt_i32_e32 vcc, s10, v42
	s_and_saveexec_b64 s[6:7], vcc
	v_add_u32_e32 v40, s11, v42
	v_ashrrev_i32_e32 v41, 31, v40
	v_lshlrev_b64 v[40:41], 11, v[40:41]
	v_lshl_add_u64 v[40:41], s[62:63], 0, v[40:41]
	v_lshl_add_u64 v[40:41], v[40:41], 0, v[0:1]
	global_load_dwordx4 v[32:35], v[40:41], off
	s_mov_b64 exec, s[4:5]
	v_add_u32_e32 v42, 28, v44
	v_mov_b32_e32 v36, 0
	v_mov_b32_e32 v37, 0
	v_mov_b32_e32 v38, 0
	v_mov_b32_e32 v39, 0
	v_cmp_lt_i32_e32 vcc, s10, v42
	s_and_saveexec_b64 s[6:7], vcc
	v_add_u32_e32 v40, s11, v42
	v_ashrrev_i32_e32 v41, 31, v40
	v_lshlrev_b64 v[40:41], 11, v[40:41]
	v_lshl_add_u64 v[40:41], s[62:63], 0, v[40:41]
	v_lshl_add_u64 v[40:41], v[40:41], 0, v[0:1]
	global_load_dwordx4 v[36:39], v[40:41], off
	s_mov_b64 exec, s[4:5]
	s_waitcnt vmcnt(0)
	v_add_u32_e32 v42, 0, v44
	v_lshl_add_u32 v43, v42, 11, v0
	ds_write_b128 v43, v[8:11]
	v_add_u32_e32 v42, 4, v44
	v_lshl_add_u32 v43, v42, 11, v0
	ds_write_b128 v43, v[12:15]
	v_add_u32_e32 v42, 8, v44
	v_lshl_add_u32 v43, v42, 11, v0
	ds_write_b128 v43, v[16:19]
	v_add_u32_e32 v42, 12, v44
	v_lshl_add_u32 v43, v42, 11, v0
	ds_write_b128 v43, v[20:23]
	v_add_u32_e32 v42, 16, v44
	v_lshl_add_u32 v43, v42, 11, v0
	ds_write_b128 v43, v[24:27]
	v_add_u32_e32 v42, 20, v44
	v_lshl_add_u32 v43, v42, 11, v0
	ds_write_b128 v43, v[28:31]
	v_add_u32_e32 v42, 24, v44
	v_lshl_add_u32 v43, v42, 11, v0
	ds_write_b128 v43, v[32:35]
	v_add_u32_e32 v42, 28, v44
	v_lshl_add_u32 v43, v42, 11, v0
	ds_write_b128 v43, v[36:39]
	v_add_u32_e32 v42, 32, v44
	v_mov_b32_e32 v8, 0
	v_mov_b32_e32 v9, 0
	v_mov_b32_e32 v10, 0
	v_mov_b32_e32 v11, 0
	v_cmp_lt_i32_e32 vcc, s10, v42
	s_and_saveexec_b64 s[6:7], vcc
	v_add_u32_e32 v40, s11, v42
	v_ashrrev_i32_e32 v41, 31, v40
	v_lshlrev_b64 v[40:41], 11, v[40:41]
	v_lshl_add_u64 v[40:41], s[62:63], 0, v[40:41]
	v_lshl_add_u64 v[40:41], v[40:41], 0, v[0:1]
	global_load_dwordx4 v[8:11], v[40:41], off
	s_mov_b64 exec, s[4:5]
	v_add_u32_e32 v42, 36, v44
	v_mov_b32_e32 v12, 0
	v_mov_b32_e32 v13, 0
	v_mov_b32_e32 v14, 0
	v_mov_b32_e32 v15, 0
	v_cmp_lt_i32_e32 vcc, s10, v42
	s_and_saveexec_b64 s[6:7], vcc
	v_add_u32_e32 v40, s11, v42
	v_ashrrev_i32_e32 v41, 31, v40
	v_lshlrev_b64 v[40:41], 11, v[40:41]
	v_lshl_add_u64 v[40:41], s[62:63], 0, v[40:41]
	v_lshl_add_u64 v[40:41], v[40:41], 0, v[0:1]
	global_load_dwordx4 v[12:15], v[40:41], off
	s_mov_b64 exec, s[4:5]
	v_add_u32_e32 v42, 40, v44
	v_mov_b32_e32 v16, 0
	v_mov_b32_e32 v17, 0
	v_mov_b32_e32 v18, 0
	v_mov_b32_e32 v19, 0
	v_cmp_lt_i32_e32 vcc, s10, v42
	s_and_saveexec_b64 s[6:7], vcc
	v_add_u32_e32 v40, s11, v42
	v_ashrrev_i32_e32 v41, 31, v40
	v_lshlrev_b64 v[40:41], 11, v[40:41]
	v_lshl_add_u64 v[40:41], s[62:63], 0, v[40:41]
	v_lshl_add_u64 v[40:41], v[40:41], 0, v[0:1]
	global_load_dwordx4 v[16:19], v[40:41], off
	s_mov_b64 exec, s[4:5]
	v_add_u32_e32 v42, 44, v44
	v_mov_b32_e32 v20, 0
	v_mov_b32_e32 v21, 0
	v_mov_b32_e32 v22, 0
	v_mov_b32_e32 v23, 0
	v_cmp_lt_i32_e32 vcc, s10, v42
	s_and_saveexec_b64 s[6:7], vcc
	v_add_u32_e32 v40, s11, v42
	v_ashrrev_i32_e32 v41, 31, v40
	v_lshlrev_b64 v[40:41], 11, v[40:41]
	v_lshl_add_u64 v[40:41], s[62:63], 0, v[40:41]
	v_lshl_add_u64 v[40:41], v[40:41], 0, v[0:1]
	global_load_dwordx4 v[20:23], v[40:41], off
	s_mov_b64 exec, s[4:5]
	v_add_u32_e32 v42, 48, v44
	v_mov_b32_e32 v24, 0
	v_mov_b32_e32 v25, 0
	v_mov_b32_e32 v26, 0
	v_mov_b32_e32 v27, 0
	v_cmp_lt_i32_e32 vcc, s10, v42
	s_and_saveexec_b64 s[6:7], vcc
	v_add_u32_e32 v40, s11, v42
	v_ashrrev_i32_e32 v41, 31, v40
	v_lshlrev_b64 v[40:41], 11, v[40:41]
	v_lshl_add_u64 v[40:41], s[62:63], 0, v[40:41]
	v_lshl_add_u64 v[40:41], v[40:41], 0, v[0:1]
	global_load_dwordx4 v[24:27], v[40:41], off
	s_mov_b64 exec, s[4:5]
	v_add_u32_e32 v42, 52, v44
	v_mov_b32_e32 v28, 0
	v_mov_b32_e32 v29, 0
	v_mov_b32_e32 v30, 0
	v_mov_b32_e32 v31, 0
	v_cmp_lt_i32_e32 vcc, s10, v42
	s_and_saveexec_b64 s[6:7], vcc
	v_add_u32_e32 v40, s11, v42
	v_ashrrev_i32_e32 v41, 31, v40
	v_lshlrev_b64 v[40:41], 11, v[40:41]
	v_lshl_add_u64 v[40:41], s[62:63], 0, v[40:41]
	v_lshl_add_u64 v[40:41], v[40:41], 0, v[0:1]
	global_load_dwordx4 v[28:31], v[40:41], off
	s_mov_b64 exec, s[4:5]
	v_add_u32_e32 v42, 56, v44
	v_mov_b32_e32 v32, 0
	v_mov_b32_e32 v33, 0
	v_mov_b32_e32 v34, 0
	v_mov_b32_e32 v35, 0
	v_cmp_lt_i32_e32 vcc, s10, v42
	s_and_saveexec_b64 s[6:7], vcc
	v_add_u32_e32 v40, s11, v42
	v_ashrrev_i32_e32 v41, 31, v40
	v_lshlrev_b64 v[40:41], 11, v[40:41]
	v_lshl_add_u64 v[40:41], s[62:63], 0, v[40:41]
	v_lshl_add_u64 v[40:41], v[40:41], 0, v[0:1]
	global_load_dwordx4 v[32:35], v[40:41], off
	s_mov_b64 exec, s[4:5]
	v_add_u32_e32 v42, 60, v44
	v_mov_b32_e32 v36, 0
	v_mov_b32_e32 v37, 0
	v_mov_b32_e32 v38, 0
	v_mov_b32_e32 v39, 0
	v_cmp_lt_i32_e32 vcc, s10, v42
	s_nop 1
	s_and_b64 vcc, vcc, s[12:13]
	s_and_saveexec_b64 s[6:7], vcc
	v_add_u32_e32 v40, s11, v42
	v_ashrrev_i32_e32 v41, 31, v40
	v_lshlrev_b64 v[40:41], 11, v[40:41]
	v_lshl_add_u64 v[40:41], s[62:63], 0, v[40:41]
	v_lshl_add_u64 v[40:41], v[40:41], 0, v[0:1]
	global_load_dwordx4 v[36:39], v[40:41], off
	s_mov_b64 exec, s[4:5]
	s_waitcnt vmcnt(0)
	v_add_u32_e32 v42, 32, v44
	v_lshl_add_u32 v43, v42, 11, v0
	ds_write_b128 v43, v[8:11]
	v_add_u32_e32 v42, 36, v44
	v_lshl_add_u32 v43, v42, 11, v0
	ds_write_b128 v43, v[12:15]
	v_add_u32_e32 v42, 40, v44
	v_lshl_add_u32 v43, v42, 11, v0
	ds_write_b128 v43, v[16:19]
	v_add_u32_e32 v42, 44, v44
	v_lshl_add_u32 v43, v42, 11, v0
	ds_write_b128 v43, v[20:23]
	v_add_u32_e32 v42, 48, v44
	v_lshl_add_u32 v43, v42, 11, v0
	ds_write_b128 v43, v[24:27]
	v_add_u32_e32 v42, 52, v44
	v_lshl_add_u32 v43, v42, 11, v0
	ds_write_b128 v43, v[28:31]
	v_add_u32_e32 v42, 56, v44
	v_lshl_add_u32 v43, v42, 11, v0
	ds_write_b128 v43, v[32:35]
	s_and_b64 exec, s[4:5], s[12:13]
	v_add_u32_e32 v42, 60, v44
	v_lshl_add_u32 v43, v42, 11, v0
	ds_write_b128 v43, v[36:39]
	s_mov_b64 exec, s[4:5]

.LBB0_810:
	v_and_b32_e32 v9, 48, v8
	v_lshlrev_b32_e32 v18, 6, v8
	s_movk_i32 s3, 0x3c0
	v_lshlrev_b32_e32 v8, 2, v8
	s_and_b32 s54, s8, 3
	s_lshl_b32 s55, s7, 6
	s_lshl_b32 s7, s7, 13
	v_and_or_b32 v9, v18, s3, v9
	v_and_b32_e32 v8, 32, v8
	v_lshl_add_u64 v[10:11], s[42:43], 0, v[0:1]
	v_mov_b32_e32 v215, v1
	v_readlane_b32 s10, v253, 52
	v_bitop3_b32 v18, v9, s7, v8 bitop3:0xde
	s_lshl_b32 s7, s54, 12
	v_lshl_add_u64 v[12:13], s[42:43], 0, v[214:215]
	v_mov_b32_e32 v219, v1
	v_readlane_b32 s11, v253, 53
	v_bitop3_b32 v244, v9, s7, v8 bitop3:0xde
	s_add_i32 m0, s50, 0x18000
	v_lshl_add_u64 v[8:9], v[10:11], 0, s[84:85]
	v_lshl_add_u64 v[14:15], s[10:11], 0, v[218:219]
	v_mov_b32_e32 v217, v1
	s_lshl_b32 s58, s54, 5
	global_load_lds_dwordx4 v[8:9], off
	v_lshl_add_u64 v[8:9], v[12:13], 0, s[84:85]
	s_add_i32 m0, s50, 0x1a000
	s_add_i32 s59, s50, 0x8000
	s_add_i32 s60, s50, 0xa000
	v_lshl_add_u64 v[16:17], s[10:11], 0, v[216:217]
	global_load_lds_dwordx4 v[8:9], off
	v_lshl_add_u64 v[8:9], v[14:15], 0, s[84:85]
	s_mov_b32 m0, s59
	s_add_u32 s8, s42, 0x40080
	global_load_lds_dwordx4 v[8:9], off
	v_lshl_add_u64 v[8:9], v[16:17], 0, s[84:85]
	s_mov_b32 m0, s60
	s_addc_u32 s9, s43, 0
	global_load_lds_dwordx4 v[8:9], off
	s_add_i32 m0, s50, 0x1c000
	v_lshl_add_u64 v[8:9], s[8:9], 0, v[0:1]
	global_load_lds_dwordx4 v[8:9], off
	v_lshl_add_u64 v[8:9], s[8:9], 0, v[214:215]
	s_add_i32 m0, s50, 0x1e000
	s_cmpk_lt_u32 s6, 0x100
	global_load_lds_dwordx4 v[8:9], off
	s_cselect_b32 s100, 1, 0
	s_cmp_lt_u32 s97, 0x100
	s_cbranch_scc1 .Lstg_skip_7
	s_barrier
.Lstg_skip_7:
	s_cmp_lg_u32 s100, 0
	s_waitcnt vmcnt(8)
	s_barrier
	v_lshlrev_b32_e32 v8, 14, v6
	v_and_b32_e32 v8, 0xffff8000, v8
	v_lshl_add_u32 v5, v5, 11, v8
	v_and_b32_e32 v6, 1, v6
	v_lshl_or_b32 v5, v6, 6, v5
	v_lshl_add_u32 v220, v7, 1, v5
	v_lshlrev_b32_e32 v5, 14, v2
	v_and_b32_e32 v5, 0xffff8000, v5
	s_waitcnt vmcnt(6)
	v_lshl_add_u32 v3, v3, 11, v5
	v_and_b32_e32 v2, 1, v2
	v_lshl_or_b32 v2, v2, 6, v3
	v_readlane_b32 s8, v253, 35
	s_cselect_b64 s[6:7], -1, 0
	v_mov_b32_e32 v221, v1
	v_lshl_add_u32 v222, v4, 1, v2
	v_mov_b32_e32 v223, v1
	s_mov_b32 s61, 0
	v_add_u32_e32 v245, 0, v18
	v_readlane_b32 s20, v253, 5
	s_mov_b32 s21, s8
	s_barrier
	v_readlane_b32 s9, v253, 36
	s_branch .LBB0_813

.LBB0_935:
	s_lshl_b32 s4, s24, 20
	s_and_b32 s4, s4, 0x100000
	v_readlane_b32 s3, v251, 49
	s_add_u32 s4, s3, s4
	v_readlane_b32 s7, v251, 50
	s_addc_u32 s5, s7, 0
	s_lshl_b32 s6, s19, 20
	s_and_b32 s6, s6, 0x100000
	v_readlane_b32 s14, v253, 23
	s_add_u32 s6, s3, s6
	v_mov_b32_e32 v199, v1
	v_readlane_b32 s15, v253, 24
	s_addc_u32 s7, s7, 0
	s_and_b32 s19, s10, 3
	s_add_i32 m0, s55, 0x18000
	v_lshl_add_u64 v[2:3], v[2:3], 0, s[84:85]
	v_lshl_add_u64 v[14:15], s[14:15], 0, v[198:199]
	v_mov_b32_e32 v197, v1
	s_lshl_b32 s61, s9, 6
	s_lshl_b32 s9, s9, 13
	s_lshl_b32 s68, s19, 5
	s_lshl_b32 s13, s19, 12
	global_load_lds_dwordx4 v[2:3], off
	v_lshl_add_u64 v[2:3], v[4:5], 0, s[84:85]
	s_add_i32 m0, s55, 0x1a000
	s_add_i32 s69, s55, 0x8000
	s_add_i32 s80, s55, 0xa000
	v_lshl_add_u64 v[16:17], s[14:15], 0, v[196:197]
	global_load_lds_dwordx4 v[2:3], off
	v_lshl_add_u64 v[2:3], v[14:15], 0, s[84:85]
	s_mov_b32 m0, s69
	s_add_u32 s10, s48, 0x40080
	global_load_lds_dwordx4 v[2:3], off
	v_lshl_add_u64 v[2:3], v[16:17], 0, s[84:85]
	s_mov_b32 m0, s80
	s_addc_u32 s11, s49, 0
	global_load_lds_dwordx4 v[2:3], off
	s_add_i32 m0, s55, 0x1c000
	v_lshl_add_u64 v[2:3], s[10:11], 0, v[0:1]
	global_load_lds_dwordx4 v[2:3], off
	v_lshl_add_u64 v[2:3], s[10:11], 0, v[194:195]
	s_add_i32 m0, s55, 0x1e000
	s_movk_i32 s3, 0x3c0
	global_load_lds_dwordx4 v[2:3], off
	s_cselect_b32 s100, 1, 0
	s_cmp_lt_u32 s97, 0x100
	s_cbranch_scc1 .Lstg_skip_8
	s_barrier
.Lstg_skip_8:
	s_cmp_lg_u32 s100, 0
	s_waitcnt vmcnt(8)
	s_barrier
	v_and_b32_e32 v2, 48, v7
	v_lshlrev_b32_e32 v3, 6, v7
	v_and_or_b32 v2, v3, s3, v2
	v_lshlrev_b32_e32 v3, 2, v7
	v_and_b32_e32 v3, 32, v3
	v_bitop3_b32 v4, v2, s9, v3 bitop3:0xde
	v_bitop3_b32 v212, v2, s13, v3 bitop3:0xde
	v_lshlrev_b32_e32 v2, 14, v11
	v_and_b32_e32 v2, 0xffff8000, v2
	v_lshl_add_u32 v2, v10, 11, v2
	v_and_b32_e32 v3, 1, v11
	v_lshl_or_b32 v2, v3, 6, v2
	v_lshl_add_u32 v200, v12, 1, v2
	v_lshlrev_b32_e32 v2, 14, v6
	v_and_b32_e32 v2, 0xffff8000, v2
	s_waitcnt vmcnt(6)
	v_lshl_add_u32 v2, v8, 11, v2
	v_and_b32_e32 v3, 1, v6
	v_readlane_b32 s10, v253, 35
	s_cmpk_lt_u32 s8, 0x100
	v_lshl_or_b32 v2, v3, 6, v2
	v_readlane_b32 s11, v253, 36
	s_mov_b32 s12, s24
	s_cselect_b64 s[8:9], -1, 0
	v_mov_b32_e32 v201, v1
	v_lshl_add_u32 v202, v9, 1, v2
	v_mov_b32_e32 v203, v1
	s_mov_b32 s81, 0
	v_add_u32_e32 v213, 0, v4
	v_readlane_b32 s82, v253, 5
	s_mov_b32 s20, s10
	s_mov_b64 s[10:11], s[14:15]
	s_barrier
	s_branch .LBB0_938
